# speedup vs baseline: 1.0460x; 1.0041x over previous
; #define NEG_INF (-__builtin_inff())
; DI void band_tile(const KV& kv, const bf16x8 (&q)[4], AState& st, const Fam& f, int n0, int tq, int wtok, float nslope) {
;   const int h2 = (TIDX & 63) >> 5;
;   f32x16 s = qk_tile(kv, q);
;   float sc[16];
;   const int nb = n0 + 8 * h2;
; #pragma unroll
;   for (int i = 0; i < 16; ++i) {
;     const int n = nb + (i & 7) + 16 * (i >> 3);
;     const int stok = n * f.kstride + f.koff;
;     const int dist = tq - stok;
;     const bool valid = (stok >= 0) && (dist >= 0) && (dist <= wtok);
;     sc[i] = valid ? s[i] + nslope * (float)dist : NEG_INF;
;   }
;   softmax_step(sc, st, kv);
; }
.LBB0_788:
	v_mfma_f32_32x32x16_bf16 v[34:49], v[34:37], v[82:85], 0
	v_mov_b32_e32 v0, v159
	s_sub_i32 s14, s49, 32
	v_lshlrev_b32_e32 v0, 2, v0
	s_cmp_gt_i32 s14, -1
	s_cselect_b64 s[46:47], -1, 0
	v_mfma_f32_32x32x16_bf16 v[34:49], v[114:117], v[86:89], v[34:49]
	v_add_u32_e32 v114, s11, v133
	v_and_b32_e32 v115, 0x80, v0
	v_sub_u32_e32 v0, v114, v115
	v_mfma_f32_32x32x16_bf16 v[34:49], v[118:121], v[90:93], v[34:49]
	v_mfma_f32_32x32x16_bf16 v[34:49], v[122:125], v[94:97], v[34:49]
	s_nop 11
	v_mov_b32_e32 v196, v0
	v_add_u32_e32 v197, -16, v0
	v_cmp_gt_u32_e32 vcc, s8, v196
	v_cmp_gt_u32_e64 s[46:47], s8, v197
	v_cvt_f32_i32_e32 v196, v196
	v_cvt_f32_i32_e32 v197, v197
	v_fma_f32 v34, -v189, v196, v34
	v_fma_f32 v35, -v189, v197, v35
	v_cndmask_b32_e32 v34, v184, v34, vcc
	v_cndmask_b32_e64 v35, v184, v35, s[46:47]
	v_add_u32_e32 v196, 0xffffffe0, v0
	v_add_u32_e32 v197, 0xffffffd0, v0
	v_cmp_gt_u32_e32 vcc, s8, v196
	v_cmp_gt_u32_e64 s[46:47], s8, v197
	v_cvt_f32_i32_e32 v196, v196
	v_cvt_f32_i32_e32 v197, v197
	v_fma_f32 v36, -v189, v196, v36
	v_fma_f32 v37, -v189, v197, v37
	v_cndmask_b32_e32 v36, v184, v36, vcc
	v_cndmask_b32_e64 v37, v184, v37, s[46:47]
	v_add_u32_e32 v196, 0xffffffc0, v0
	v_add_u32_e32 v197, 0xffffffb0, v0
	v_cmp_gt_u32_e32 vcc, s8, v196
	v_cmp_gt_u32_e64 s[46:47], s8, v197
	v_cvt_f32_i32_e32 v196, v196
	v_cvt_f32_i32_e32 v197, v197
	v_fma_f32 v38, -v189, v196, v38
	v_fma_f32 v39, -v189, v197, v39
	v_cndmask_b32_e32 v38, v184, v38, vcc
	v_cndmask_b32_e64 v39, v184, v39, s[46:47]
	v_add_u32_e32 v196, 0xffffffa0, v0
	v_add_u32_e32 v197, 0xffffff90, v0
	v_cmp_gt_u32_e32 vcc, s8, v196
	v_cmp_gt_u32_e64 s[46:47], s8, v197
	v_cvt_f32_i32_e32 v196, v196
	v_cvt_f32_i32_e32 v197, v197
	v_fma_f32 v40, -v189, v196, v40
	v_fma_f32 v41, -v189, v197, v41
	v_cndmask_b32_e32 v40, v184, v40, vcc
	v_cndmask_b32_e64 v41, v184, v41, s[46:47]
	v_add_u32_e32 v196, 0xffffff00, v0
	v_add_u32_e32 v197, 0xfffffef0, v0
	v_cmp_gt_u32_e32 vcc, s8, v196
	v_cmp_gt_u32_e64 s[46:47], s8, v197
	v_cvt_f32_i32_e32 v196, v196
	v_cvt_f32_i32_e32 v197, v197
	v_fma_f32 v42, -v189, v196, v42
	v_fma_f32 v43, -v189, v197, v43
	v_cndmask_b32_e32 v42, v184, v42, vcc
	v_cndmask_b32_e64 v43, v184, v43, s[46:47]
	v_add_u32_e32 v196, 0xfffffee0, v0
	v_add_u32_e32 v197, 0xfffffed0, v0
	v_cmp_gt_u32_e32 vcc, s8, v196
	v_cmp_gt_u32_e64 s[46:47], s8, v197
	v_cvt_f32_i32_e32 v196, v196
	v_cvt_f32_i32_e32 v197, v197
	v_fma_f32 v44, -v189, v196, v44
	v_fma_f32 v45, -v189, v197, v45
	v_cndmask_b32_e32 v44, v184, v44, vcc
	v_cndmask_b32_e64 v45, v184, v45, s[46:47]
	v_add_u32_e32 v196, 0xfffffec0, v0
	v_add_u32_e32 v197, 0xfffffeb0, v0
	v_cmp_gt_u32_e32 vcc, s8, v196
	v_cmp_gt_u32_e64 s[46:47], s8, v197
	v_cvt_f32_i32_e32 v196, v196
	v_cvt_f32_i32_e32 v197, v197
	v_fma_f32 v46, -v189, v196, v46
	v_fma_f32 v47, -v189, v197, v47
	v_cndmask_b32_e32 v46, v184, v46, vcc
	v_cndmask_b32_e64 v47, v184, v47, s[46:47]
	v_add_u32_e32 v196, 0xfffffea0, v0
	v_add_u32_e32 v197, 0xfffffe90, v0
	v_cmp_gt_u32_e32 vcc, s8, v196
	v_cmp_gt_u32_e64 s[46:47], s8, v197
	v_cvt_f32_i32_e32 v196, v196
	v_cvt_f32_i32_e32 v197, v197
	v_fma_f32 v48, -v189, v196, v48
	v_fma_f32 v49, -v189, v197, v49
	v_cndmask_b32_e32 v48, v184, v48, vcc
	v_cndmask_b32_e64 v49, v184, v49, s[46:47]
	v_max3_f32 v0, v34, s35, v35
	v_max3_f32 v0, v0, v36, v37
	v_max3_f32 v0, v0, v38, v39
	v_mbcnt_hi_u32_b32 v114, -1, v180
	v_max3_f32 v0, v0, v40, v41
	v_and_b32_e32 v116, 64, v114
	v_max3_f32 v0, v0, v42, v43
	v_xor_b32_e32 v115, 32, v114
	v_add_u32_e32 v116, 64, v116
	v_max3_f32 v0, v0, v44, v45
	v_cmp_lt_i32_e32 vcc, v115, v116
	v_max3_f32 v0, v0, v46, v47
	v_max3_f32 v0, v0, v48, v49
	v_cndmask_b32_e32 v114, v114, v115, vcc
	v_lshlrev_b32_e32 v114, 2, v114
	ds_bpermute_b32 v114, v114, v0
	s_waitcnt lgkmcnt(0)
	v_max3_f32 v131, v135, v0, v114
	v_cmp_neq_f32_e32 vcc, s35, v131
	s_nop 1
	v_cndmask_b32_e32 v114, 0, v131, vcc
	v_sub_f32_e32 v0, v135, v114
	v_mul_f32_e32 v0, 0x3fb8aa3b, v0
	v_exp_f32_e32 v0, v0
	s_nop 0
	v_cmp_neq_f32_e32 vcc, 1.0, v0
	s_cbranch_vccz .LBB0_790
	v_pk_mul_f32 v[32:33], v[32:33], v[0:1] op_sel_hi:[1,0]
	v_pk_mul_f32 v[30:31], v[30:31], v[0:1] op_sel_hi:[1,0]
	v_pk_mul_f32 v[28:29], v[28:29], v[0:1] op_sel_hi:[1,0]
	v_pk_mul_f32 v[26:27], v[26:27], v[0:1] op_sel_hi:[1,0]
	v_pk_mul_f32 v[24:25], v[24:25], v[0:1] op_sel_hi:[1,0]
	v_pk_mul_f32 v[22:23], v[22:23], v[0:1] op_sel_hi:[1,0]
	v_pk_mul_f32 v[20:21], v[20:21], v[0:1] op_sel_hi:[1,0]
	v_pk_mul_f32 v[18:19], v[18:19], v[0:1] op_sel_hi:[1,0]
	v_pk_mul_f32 v[16:17], v[16:17], v[0:1] op_sel_hi:[1,0]
	v_pk_mul_f32 v[14:15], v[14:15], v[0:1] op_sel_hi:[1,0]
	v_pk_mul_f32 v[12:13], v[12:13], v[0:1] op_sel_hi:[1,0]
	v_pk_mul_f32 v[10:11], v[10:11], v[0:1] op_sel_hi:[1,0]
	v_pk_mul_f32 v[8:9], v[8:9], v[0:1] op_sel_hi:[1,0]
	v_pk_mul_f32 v[6:7], v[6:7], v[0:1] op_sel_hi:[1,0]
	v_pk_mul_f32 v[4:5], v[4:5], v[0:1] op_sel_hi:[1,0]
	v_pk_mul_f32 v[2:3], v[2:3], v[0:1] op_sel_hi:[1,0]

; #define NEG_INF (-__builtin_inff())
; DI void band_tile(const KV& kv, const bf16x8 (&q)[4], AState& st, const Fam& f, int n0, int tq, int wtok, float nslope) {
;   const int h2 = (TIDX & 63) >> 5;
;   f32x16 s = qk_tile(kv, q);
;   float sc[16];
;   const int nb = n0 + 8 * h2;
; #pragma unroll
;   for (int i = 0; i < 16; ++i) {
;     const int n = nb + (i & 7) + 16 * (i >> 3);
;     const int stok = n * f.kstride + f.koff;
;     const int dist = tq - stok;
;     const bool valid = (stok >= 0) && (dist >= 0) && (dist <= wtok);
;     sc[i] = valid ? s[i] + nslope * (float)dist : NEG_INF;
;   }
;   softmax_step(sc, st, kv);
; }
.LBB0_796:
	v_mfma_f32_32x32x16_bf16 v[34:49], v[34:37], v[82:85], 0
	v_mov_b32_e32 v0, v159
	s_sub_i32 s14, s10, 32
	s_cmp_gt_i32 s14, -1
	s_cselect_b64 s[46:47], -1, 0
	v_mfma_f32_32x32x16_bf16 v[34:49], v[114:117], v[86:89], v[34:49]
	v_and_b32_e32 v114, 32, v0
	v_add_u32_e32 v0, s23, v133
	v_sub_u32_e32 v0, v0, v114
	v_mfma_f32_32x32x16_bf16 v[34:49], v[118:121], v[90:93], v[34:49]
	v_mfma_f32_32x32x16_bf16 v[34:49], v[122:125], v[94:97], v[34:49]
	s_nop 11
	v_mov_b32_e32 v196, v0
	v_add_u32_e32 v197, -4, v0
	v_cmp_gt_u32_e32 vcc, s34, v196
	v_cmp_gt_u32_e64 s[46:47], s34, v197
	v_cvt_f32_i32_e32 v196, v196
	v_cvt_f32_i32_e32 v197, v197
	v_fma_f32 v34, -v189, v196, v34
	v_fma_f32 v35, -v189, v197, v35
	v_cndmask_b32_e32 v34, v184, v34, vcc
	v_cndmask_b32_e64 v35, v184, v35, s[46:47]
	v_add_u32_e32 v196, -8, v0
	v_add_u32_e32 v197, -12, v0
	v_cmp_gt_u32_e32 vcc, s34, v196
	v_cmp_gt_u32_e64 s[46:47], s34, v197
	v_cvt_f32_i32_e32 v196, v196
	v_cvt_f32_i32_e32 v197, v197
	v_fma_f32 v36, -v189, v196, v36
	v_fma_f32 v37, -v189, v197, v37
	v_cndmask_b32_e32 v36, v184, v36, vcc
	v_cndmask_b32_e64 v37, v184, v37, s[46:47]
	v_add_u32_e32 v196, -16, v0
	v_add_u32_e32 v197, 0xffffffec, v0
	v_cmp_gt_u32_e32 vcc, s34, v196
	v_cmp_gt_u32_e64 s[46:47], s34, v197
	v_cvt_f32_i32_e32 v196, v196
	v_cvt_f32_i32_e32 v197, v197
	v_fma_f32 v38, -v189, v196, v38
	v_fma_f32 v39, -v189, v197, v39
	v_cndmask_b32_e32 v38, v184, v38, vcc
	v_cndmask_b32_e64 v39, v184, v39, s[46:47]
	v_add_u32_e32 v196, 0xffffffe8, v0
	v_add_u32_e32 v197, 0xffffffe4, v0
	v_cmp_gt_u32_e32 vcc, s34, v196
	v_cmp_gt_u32_e64 s[46:47], s34, v197
	v_cvt_f32_i32_e32 v196, v196
	v_cvt_f32_i32_e32 v197, v197
	v_fma_f32 v40, -v189, v196, v40
	v_fma_f32 v41, -v189, v197, v41
	v_cndmask_b32_e32 v40, v184, v40, vcc
	v_cndmask_b32_e64 v41, v184, v41, s[46:47]
	v_add_u32_e32 v196, 0xffffffc0, v0
	v_add_u32_e32 v197, 0xffffffbc, v0
	v_cmp_gt_u32_e32 vcc, s34, v196
	v_cmp_gt_u32_e64 s[46:47], s34, v197
	v_cvt_f32_i32_e32 v196, v196
	v_cvt_f32_i32_e32 v197, v197
	v_fma_f32 v42, -v189, v196, v42
	v_fma_f32 v43, -v189, v197, v43
	v_cndmask_b32_e32 v42, v184, v42, vcc
	v_cndmask_b32_e64 v43, v184, v43, s[46:47]
	v_add_u32_e32 v196, 0xffffffb8, v0
	v_add_u32_e32 v197, 0xffffffb4, v0
	v_cmp_gt_u32_e32 vcc, s34, v196
	v_cmp_gt_u32_e64 s[46:47], s34, v197
	v_cvt_f32_i32_e32 v196, v196
	v_cvt_f32_i32_e32 v197, v197
	v_fma_f32 v44, -v189, v196, v44
	v_fma_f32 v45, -v189, v197, v45
	v_cndmask_b32_e32 v44, v184, v44, vcc
	v_cndmask_b32_e64 v45, v184, v45, s[46:47]
	v_add_u32_e32 v196, 0xffffffb0, v0
	v_add_u32_e32 v197, 0xffffffac, v0
	v_cmp_gt_u32_e32 vcc, s34, v196
	v_cmp_gt_u32_e64 s[46:47], s34, v197
	v_cvt_f32_i32_e32 v196, v196
	v_cvt_f32_i32_e32 v197, v197
	v_fma_f32 v46, -v189, v196, v46
	v_fma_f32 v47, -v189, v197, v47
	v_cndmask_b32_e32 v46, v184, v46, vcc
	v_cndmask_b32_e64 v47, v184, v47, s[46:47]
	v_add_u32_e32 v196, 0xffffffa8, v0
	v_add_u32_e32 v197, 0xffffffa4, v0
	v_cmp_gt_u32_e32 vcc, s34, v196
	v_cmp_gt_u32_e64 s[46:47], s34, v197
	v_cvt_f32_i32_e32 v196, v196
	v_cvt_f32_i32_e32 v197, v197
	v_fma_f32 v48, -v189, v196, v48
	v_fma_f32 v49, -v189, v197, v49
	v_cndmask_b32_e32 v48, v184, v48, vcc
	v_cndmask_b32_e64 v49, v184, v49, s[46:47]
	v_max3_f32 v0, v34, s35, v35
	v_max3_f32 v0, v0, v36, v37
	v_max3_f32 v0, v0, v38, v39
	v_mbcnt_hi_u32_b32 v114, -1, v180
	v_max3_f32 v0, v0, v40, v41
	v_and_b32_e32 v116, 64, v114
	v_max3_f32 v0, v0, v42, v43
	v_xor_b32_e32 v115, 32, v114
	v_add_u32_e32 v116, 64, v116
	v_max3_f32 v0, v0, v44, v45
	v_cmp_lt_i32_e32 vcc, v115, v116
	v_max3_f32 v0, v0, v46, v47
	v_max3_f32 v0, v0, v48, v49
	v_cndmask_b32_e32 v114, v114, v115, vcc
	v_lshlrev_b32_e32 v114, 2, v114
	ds_bpermute_b32 v114, v114, v0
	s_waitcnt lgkmcnt(0)
	v_max3_f32 v191, v131, v0, v114
	v_cmp_neq_f32_e32 vcc, s35, v191
	s_nop 1
	v_cndmask_b32_e32 v114, 0, v191, vcc
	v_sub_f32_e32 v0, v131, v114
	v_mul_f32_e32 v0, 0x3fb8aa3b, v0
	v_exp_f32_e32 v0, v0
	s_nop 0
	v_cmp_neq_f32_e32 vcc, 1.0, v0
	s_cbranch_vccz .LBB0_798
	v_pk_mul_f32 v[32:33], v[32:33], v[0:1] op_sel_hi:[1,0]
	v_pk_mul_f32 v[30:31], v[30:31], v[0:1] op_sel_hi:[1,0]
	v_pk_mul_f32 v[28:29], v[28:29], v[0:1] op_sel_hi:[1,0]
	v_pk_mul_f32 v[26:27], v[26:27], v[0:1] op_sel_hi:[1,0]
	v_pk_mul_f32 v[24:25], v[24:25], v[0:1] op_sel_hi:[1,0]
	v_pk_mul_f32 v[22:23], v[22:23], v[0:1] op_sel_hi:[1,0]
	v_pk_mul_f32 v[20:21], v[20:21], v[0:1] op_sel_hi:[1,0]
	v_pk_mul_f32 v[18:19], v[18:19], v[0:1] op_sel_hi:[1,0]
	v_pk_mul_f32 v[16:17], v[16:17], v[0:1] op_sel_hi:[1,0]
	v_pk_mul_f32 v[14:15], v[14:15], v[0:1] op_sel_hi:[1,0]
	v_pk_mul_f32 v[12:13], v[12:13], v[0:1] op_sel_hi:[1,0]
	v_pk_mul_f32 v[10:11], v[10:11], v[0:1] op_sel_hi:[1,0]
	v_pk_mul_f32 v[8:9], v[8:9], v[0:1] op_sel_hi:[1,0]
	v_pk_mul_f32 v[6:7], v[6:7], v[0:1] op_sel_hi:[1,0]
	v_pk_mul_f32 v[4:5], v[4:5], v[0:1] op_sel_hi:[1,0]
	v_pk_mul_f32 v[2:3], v[2:3], v[0:1] op_sel_hi:[1,0]

; #define NEG_INF (-__builtin_inff())
; DI void band_tile(const KV& kv, const bf16x8 (&q)[4], AState& st, const Fam& f, int n0, int tq, int wtok, float nslope) {
;   const int h2 = (TIDX & 63) >> 5;
;   f32x16 s = qk_tile(kv, q);
;   float sc[16];
;   const int nb = n0 + 8 * h2;
; #pragma unroll
;   for (int i = 0; i < 16; ++i) {
;     const int n = nb + (i & 7) + 16 * (i >> 3);
;     const int stok = n * f.kstride + f.koff;
;     const int dist = tq - stok;
;     const bool valid = (stok >= 0) && (dist >= 0) && (dist <= wtok);
;     sc[i] = valid ? s[i] + nslope * (float)dist : NEG_INF;
;   }
;   softmax_step(sc, st, kv);
; }
.LBB0_804:
	v_mfma_f32_32x32x16_bf16 v[66:81], v[66:69], v[82:85], 0
	v_mov_b32_e32 v0, v159
	s_cmp_gt_i32 s10, -1
	v_lshrrev_b32_e32 v0, 2, v0
	s_cselect_b64 s[46:47], -1, 0
	s_movk_i32 s14, 0xffef
	v_mfma_f32_32x32x16_bf16 v[66:81], v[146:149], v[86:89], v[66:81]
	v_and_b32_e32 v146, 8, v0
	v_add_u32_e32 v147, s12, v192
	v_sub_u32_e32 v146, v147, v146
	v_mfma_f32_32x32x16_bf16 v[66:81], v[150:153], v[90:93], v[66:81]
	v_mfma_f32_32x32x16_bf16 v[66:81], v[154:157], v[94:97], v[66:81]
	s_nop 11
	v_mov_b32_e32 v196, v146
	v_add_u32_e32 v197, -1, v146
	v_cmp_gt_u32_e32 vcc, s9, v196
	v_cmp_gt_u32_e64 s[46:47], s9, v197
	v_cvt_f32_i32_e32 v196, v196
	v_cvt_f32_i32_e32 v197, v197
	v_fma_f32 v66, -v189, v196, v66
	v_fma_f32 v67, -v189, v197, v67
	v_cndmask_b32_e32 v66, v184, v66, vcc
	v_cndmask_b32_e64 v67, v184, v67, s[46:47]
	v_add_u32_e32 v196, -2, v146
	v_add_u32_e32 v197, -3, v146
	v_cmp_gt_u32_e32 vcc, s9, v196
	v_cmp_gt_u32_e64 s[46:47], s9, v197
	v_cvt_f32_i32_e32 v196, v196
	v_cvt_f32_i32_e32 v197, v197
	v_fma_f32 v68, -v189, v196, v68
	v_fma_f32 v69, -v189, v197, v69
	v_cndmask_b32_e32 v68, v184, v68, vcc
	v_cndmask_b32_e64 v69, v184, v69, s[46:47]
	v_add_u32_e32 v196, -4, v146
	v_add_u32_e32 v197, -5, v146
	v_cmp_gt_u32_e32 vcc, s9, v196
	v_cmp_gt_u32_e64 s[46:47], s9, v197
	v_cvt_f32_i32_e32 v196, v196
	v_cvt_f32_i32_e32 v197, v197
	v_fma_f32 v70, -v189, v196, v70
	v_fma_f32 v71, -v189, v197, v71
	v_cndmask_b32_e32 v70, v184, v70, vcc
	v_cndmask_b32_e64 v71, v184, v71, s[46:47]
	v_add_u32_e32 v196, -6, v146
	v_add_u32_e32 v197, -7, v146
	v_cmp_gt_u32_e32 vcc, s9, v196
	v_cmp_gt_u32_e64 s[46:47], s9, v197
	v_cvt_f32_i32_e32 v196, v196
	v_cvt_f32_i32_e32 v197, v197
	v_fma_f32 v72, -v189, v196, v72
	v_fma_f32 v73, -v189, v197, v73
	v_cndmask_b32_e32 v72, v184, v72, vcc
	v_cndmask_b32_e64 v73, v184, v73, s[46:47]
	v_add_u32_e32 v196, -16, v146
	v_add_u32_e32 v197, 0xffffffef, v146
	v_cmp_gt_u32_e32 vcc, s9, v196
	v_cmp_gt_u32_e64 s[46:47], s9, v197
	v_cvt_f32_i32_e32 v196, v196
	v_cvt_f32_i32_e32 v197, v197
	v_fma_f32 v74, -v189, v196, v74
	v_fma_f32 v75, -v189, v197, v75
	v_cndmask_b32_e32 v74, v184, v74, vcc
	v_cndmask_b32_e64 v75, v184, v75, s[46:47]
	v_add_u32_e32 v196, 0xffffffee, v146
	v_add_u32_e32 v197, 0xffffffed, v146
	v_cmp_gt_u32_e32 vcc, s9, v196
	v_cmp_gt_u32_e64 s[46:47], s9, v197
	v_cvt_f32_i32_e32 v196, v196
	v_cvt_f32_i32_e32 v197, v197
	v_fma_f32 v76, -v189, v196, v76
	v_fma_f32 v77, -v189, v197, v77
	v_cndmask_b32_e32 v76, v184, v76, vcc
	v_cndmask_b32_e64 v77, v184, v77, s[46:47]
	v_add_u32_e32 v196, 0xffffffec, v146
	v_add_u32_e32 v197, 0xffffffeb, v146
	v_cmp_gt_u32_e32 vcc, s9, v196
	v_cmp_gt_u32_e64 s[46:47], s9, v197
	v_cvt_f32_i32_e32 v196, v196
	v_cvt_f32_i32_e32 v197, v197
	v_fma_f32 v78, -v189, v196, v78
	v_fma_f32 v147, -v189, v197, v79
	v_cndmask_b32_e32 v78, v184, v78, vcc
	v_cndmask_b32_e64 v147, v184, v147, s[46:47]
	v_add_u32_e32 v196, 0xffffffea, v146
	v_add_u32_e32 v197, 0xffffffe9, v146
	v_cmp_gt_u32_e32 vcc, s9, v196
	v_cmp_gt_u32_e64 s[46:47], s9, v197
	v_cvt_f32_i32_e32 v196, v196
	v_cvt_f32_i32_e32 v197, v197
	v_fma_f32 v148, -v189, v196, v80
	v_fma_f32 v149, -v189, v197, v81
	v_cndmask_b32_e32 v148, v184, v148, vcc
	v_cndmask_b32_e64 v149, v184, v149, s[46:47]
	v_mbcnt_hi_u32_b32 v79, -1, v180
	v_max3_f32 v0, v66, s35, v67
	v_max3_f32 v0, v0, v68, v69
	v_max3_f32 v0, v0, v70, v71
	v_max3_f32 v0, v0, v72, v73
	v_and_b32_e32 v81, 64, v79
	v_max3_f32 v0, v0, v74, v75
	v_xor_b32_e32 v80, 32, v79
	v_add_u32_e32 v81, 64, v81
	v_max3_f32 v0, v0, v76, v77
	v_cmp_lt_i32_e32 vcc, v80, v81
	v_max3_f32 v0, v0, v78, v147
	v_max3_f32 v0, v0, v148, v149
	v_cndmask_b32_e32 v146, v79, v80, vcc
	v_lshlrev_b32_e32 v146, 2, v146
	ds_bpermute_b32 v146, v146, v0
	s_waitcnt lgkmcnt(0)
	v_max3_f32 v146, v191, v0, v146
	v_cmp_neq_f32_e32 vcc, s35, v146
	s_nop 1
	v_cndmask_b32_e32 v150, 0, v146, vcc
	v_sub_f32_e32 v0, v191, v150
	v_mul_f32_e32 v0, 0x3fb8aa3b, v0
	v_exp_f32_e32 v0, v0
	s_nop 0
	v_cmp_neq_f32_e32 vcc, 1.0, v0
	s_cbranch_vccz .LBB0_806
	v_pk_mul_f32 v[64:65], v[64:65], v[0:1] op_sel_hi:[1,0]
	v_pk_mul_f32 v[62:63], v[62:63], v[0:1] op_sel_hi:[1,0]
	v_pk_mul_f32 v[60:61], v[60:61], v[0:1] op_sel_hi:[1,0]
	v_pk_mul_f32 v[58:59], v[58:59], v[0:1] op_sel_hi:[1,0]
	v_pk_mul_f32 v[56:57], v[56:57], v[0:1] op_sel_hi:[1,0]
	v_pk_mul_f32 v[54:55], v[54:55], v[0:1] op_sel_hi:[1,0]
	v_pk_mul_f32 v[52:53], v[52:53], v[0:1] op_sel_hi:[1,0]
	v_pk_mul_f32 v[50:51], v[50:51], v[0:1] op_sel_hi:[1,0]
	v_pk_mul_f32 v[48:49], v[48:49], v[0:1] op_sel_hi:[1,0]
	v_pk_mul_f32 v[46:47], v[46:47], v[0:1] op_sel_hi:[1,0]
	v_pk_mul_f32 v[44:45], v[44:45], v[0:1] op_sel_hi:[1,0]
	v_pk_mul_f32 v[42:43], v[42:43], v[0:1] op_sel_hi:[1,0]
	v_pk_mul_f32 v[40:41], v[40:41], v[0:1] op_sel_hi:[1,0]
	v_pk_mul_f32 v[38:39], v[38:39], v[0:1] op_sel_hi:[1,0]
	v_pk_mul_f32 v[36:37], v[36:37], v[0:1] op_sel_hi:[1,0]
	v_pk_mul_f32 v[34:35], v[34:35], v[0:1] op_sel_hi:[1,0]
